# selected-branch loop: s_setprio 1/0 bracket each QK and PV MFMA burst so the MFMA-issuing wave wins arbitration over its SIMD partner's VALU stream
# speedup vs baseline: 1.0100x; 1.0050x over previous
.LBB0_419:
	s_cmp_eq_u32 s13, s12
	s_cbranch_scc1 .LBB0_418
	s_or_b32 s6, s13, s5
	s_ff1_i32_b64 s18, s[8:9]
	s_lshl_b32 s6, s6, 14
	s_and_b32 s6, s6, 0xc000
	s_lshl_b32 s14, s18, 6
	s_add_i32 s13, s6, 0
	s_or_b32 s16, s14, 63
	s_mov_b64 s[6:7], -1
	s_cmp_ge_i32 s16, s1
	v_lshrrev_b64 v[162:163], s18, v[38:39]
	v_lshrrev_b64 v[164:165], s18, v[40:41]
	s_cbranch_scc0 .LBB0_439
	s_cmp_le_i32 s16, s2
	s_cselect_b64 s[6:7], -1, 0
	s_cmp_gt_i32 s14, s4
	v_and_b32_e32 v0, 1, v164
	s_cselect_b64 s[18:19], -1, 0
	v_cmp_eq_u32_e64 s[42:43], 1, v0
	v_and_b32_e32 v0, 1, v162
	s_and_b64 s[18:19], s[6:7], s[18:19]
	v_cmp_eq_u32_e64 s[44:45], 1, v0
	s_andn2_b64 vcc, exec, s[18:19]
	s_or_b64 s[18:19], s[44:45], s[42:43]
	s_mov_b64 s[6:7], -1
	v_cndmask_b32_e64 v139, 0, 1, s[18:19]
	s_cbranch_vccz .LBB0_430
	v_cmp_ne_u32_e32 vcc, 0, v139
	s_cbranch_vccz .Lsel_fast
	v_add_u32_e32 v54, s13, v196
	v_cmp_ne_u32_e32 vcc, 0, v0
	v_sub_u32_e32 v0, s14, v140
	v_add_u32_e32 v62, v54, v194
	v_add_u32_e32 v89, v54, v195
	v_lshl_add_u32 v0, v0, 2, v216
	s_cbranch_vccz .Lp0_skip0
	v_add_u32_e32 v63, 0xffc, v0
	ds_read_b128 v[54:57], v62 offset:16384
	ds_read_b128 v[58:61], v62 offset:18432
	ds_read_b128 v[64:67], v62 offset:20480
	ds_read_b128 v[68:71], v89 offset:16384
	ds_read_b128 v[72:75], v62 offset:22528
	ds_read2_b32 v[90:91], v63 offset1:1
	ds_read2_b32 v[92:93], v63 offset0:2 offset1:3
	ds_read2_b32 v[94:95], v63 offset0:16 offset1:17
	ds_read2_b32 v[96:97], v63 offset0:18 offset1:19
	ds_read2_b32 v[98:99], v63 offset0:32 offset1:33
	ds_read2_b32 v[100:101], v63 offset0:34 offset1:35
	ds_read2_b32 v[154:155], v63 offset0:48 offset1:49
	ds_read2_b32 v[156:157], v63 offset0:50 offset1:51
	s_waitcnt lgkmcnt(8)
	s_setprio 1
	v_mfma_f32_16x16x32_bf16 v[54:57], v[54:57], v[2:5], 0
	v_mfma_f32_16x16x32_bf16 v[58:61], v[58:61], v[2:5], 0
	v_mfma_f32_16x16x32_bf16 v[54:57], v[68:71], v[6:9], v[54:57]
	ds_read_b128 v[68:71], v89 offset:18432
	ds_read_b128 v[76:79], v89 offset:20480
	v_mfma_f32_16x16x32_bf16 v[64:67], v[64:67], v[2:5], 0
	v_mfma_f32_16x16x32_bf16 v[84:87], v[72:75], v[2:5], 0
	s_waitcnt lgkmcnt(0)
	v_mfma_f32_16x16x32_bf16 v[58:61], v[68:71], v[6:9], v[58:61]
	ds_read_b128 v[68:71], v89 offset:22528
	v_mfma_f32_16x16x32_bf16 v[64:67], v[76:79], v[6:9], v[64:67]
	s_waitcnt lgkmcnt(0)
	v_mfma_f32_16x16x32_bf16 v[84:87], v[68:71], v[6:9], v[84:87]
	s_setprio 0
	v_pk_fma_f32 v[54:55], v[54:55], s[36:37], v[90:91] op_sel_hi:[1,0,1]
	v_pk_fma_f32 v[56:57], v[56:57], s[36:37], v[92:93] op_sel_hi:[1,0,1]
	s_nop 1
	v_pk_fma_f32 v[58:59], v[58:59], s[36:37], v[94:95] op_sel_hi:[1,0,1]
	v_pk_fma_f32 v[60:61], v[60:61], s[36:37], v[96:97] op_sel_hi:[1,0,1]
	v_pk_fma_f32 v[64:65], v[64:65], s[36:37], v[98:99] op_sel_hi:[1,0,1]
	v_pk_fma_f32 v[66:67], v[66:67], s[36:37], v[100:101] op_sel_hi:[1,0,1]
	v_pk_fma_f32 v[84:85], v[84:85], s[36:37], v[154:155] op_sel_hi:[1,0,1]
	v_pk_fma_f32 v[86:87], v[86:87], s[36:37], v[156:157] op_sel_hi:[1,0,1]
	v_or_b32_e32 v83, s14, v197
	v_sub_u32_e32 v88, v140, v83
	v_cmp_le_i32_e64 s[6:7], 0, v88
	v_cmp_le_i32_e64 s[18:19], 1, v88
	v_cmp_le_i32_e64 s[98:99], 2, v88
	v_cmp_le_i32_e64 s[100:101], 3, v88
	v_cndmask_b32_e64 v54, v148, v54, s[6:7]
	v_cndmask_b32_e64 v55, v148, v55, s[18:19]
	v_cndmask_b32_e64 v56, v148, v56, s[98:99]
	v_cndmask_b32_e64 v57, v148, v57, s[100:101]
	v_cmp_le_i32_e64 s[6:7], 16, v88
	v_cmp_le_i32_e64 s[18:19], 17, v88
	v_cmp_le_i32_e64 s[98:99], 18, v88
	v_cmp_le_i32_e64 s[100:101], 19, v88
	v_cndmask_b32_e64 v58, v148, v58, s[6:7]
	v_cndmask_b32_e64 v59, v148, v59, s[18:19]
	v_cndmask_b32_e64 v60, v148, v60, s[98:99]
	v_cndmask_b32_e64 v61, v148, v61, s[100:101]
	v_cmp_le_i32_e64 s[6:7], 32, v88
	v_cmp_le_i32_e64 s[18:19], 33, v88
	v_cmp_le_i32_e64 s[98:99], 34, v88
	v_cmp_le_i32_e64 s[100:101], 35, v88
	v_cndmask_b32_e64 v64, v148, v64, s[6:7]
	v_cndmask_b32_e64 v65, v148, v65, s[18:19]
	v_cndmask_b32_e64 v66, v148, v66, s[98:99]
	v_cndmask_b32_e64 v67, v148, v67, s[100:101]
	v_cmp_le_i32_e64 s[6:7], 48, v88
	v_cmp_le_i32_e64 s[18:19], 49, v88
	v_cmp_le_i32_e64 s[98:99], 50, v88
	v_cmp_le_i32_e64 s[100:101], 51, v88
	v_cndmask_b32_e64 v84, v148, v84, s[6:7]
	v_cndmask_b32_e64 v85, v148, v85, s[18:19]
	v_cndmask_b32_e64 v86, v148, v86, s[98:99]
	v_cndmask_b32_e64 v87, v148, v87, s[100:101]
	v_max3_f32 v63, v54, v55, v56
	v_max3_f32 v63, v63, v57, v58
	v_max3_f32 v63, v63, v59, v60
	v_max3_f32 v63, v63, v61, v64
	v_max3_f32 v63, v63, v65, v66
	v_max3_f32 v63, v63, v67, v84
	v_max3_f32 v63, v63, v85, v86
	v_max3_f32 v63, v63, v87, s29
	v_mov_b32_e32 v68, v63
	s_nop 1
	v_permlane16_swap_b32_e32 v63, v68
	v_max_f32_e32 v63, v63, v68
	v_mov_b32_e32 v68, v63
	s_nop 1
	v_permlane32_swap_b32_e32 v63, v68
	v_max_f32_e32 v63, v63, v68
	v_cndmask_b32_e64 v63, v148, v63, s[44:45]
	v_max_f32_e32 v68, v160, v63
	v_sub_f32_e32 v69, v160, v68
	v_exp_f32_e32 v70, v69
	v_cndmask_b32_e64 v82, v209, v68, s[44:45]
	v_mov_b32_e32 v160, v68
	v_pk_mul_f32 v[36:37], v[36:37], v[70:71] op_sel_hi:[1,0]
	v_pk_mul_f32 v[34:35], v[34:35], v[70:71] op_sel_hi:[1,0]
	v_pk_mul_f32 v[48:49], v[48:49], v[70:71] op_sel_hi:[1,0]
	v_pk_mul_f32 v[46:47], v[46:47], v[70:71] op_sel_hi:[1,0]
	v_pk_mul_f32 v[44:45], v[44:45], v[70:71] op_sel_hi:[1,0]
	v_pk_mul_f32 v[42:43], v[42:43], v[70:71] op_sel_hi:[1,0]
	v_pk_mul_f32 v[52:53], v[52:53], v[70:71] op_sel_hi:[1,0]
	v_pk_mul_f32 v[50:51], v[50:51], v[70:71] op_sel_hi:[1,0]
	v_pk_add_f32 v[54:55], v[54:55], v[82:83] op_sel_hi:[1,0] neg_lo:[0,1] neg_hi:[0,1]
	v_pk_add_f32 v[56:57], v[56:57], v[82:83] op_sel_hi:[1,0] neg_lo:[0,1] neg_hi:[0,1]
	v_pk_add_f32 v[58:59], v[58:59], v[82:83] op_sel_hi:[1,0] neg_lo:[0,1] neg_hi:[0,1]
	v_pk_add_f32 v[60:61], v[60:61], v[82:83] op_sel_hi:[1,0] neg_lo:[0,1] neg_hi:[0,1]
	v_pk_add_f32 v[64:65], v[64:65], v[82:83] op_sel_hi:[1,0] neg_lo:[0,1] neg_hi:[0,1]
	v_pk_add_f32 v[66:67], v[66:67], v[82:83] op_sel_hi:[1,0] neg_lo:[0,1] neg_hi:[0,1]
	v_pk_add_f32 v[84:85], v[84:85], v[82:83] op_sel_hi:[1,0] neg_lo:[0,1] neg_hi:[0,1]
	v_pk_add_f32 v[86:87], v[86:87], v[82:83] op_sel_hi:[1,0] neg_lo:[0,1] neg_hi:[0,1]
	v_exp_f32_e32 v54, v54
	v_exp_f32_e32 v55, v55
	v_exp_f32_e32 v56, v56
	v_exp_f32_e32 v57, v57
	v_exp_f32_e32 v58, v58
	v_exp_f32_e32 v59, v59
	v_exp_f32_e32 v60, v60
	v_exp_f32_e32 v61, v61
	v_exp_f32_e32 v64, v64
	v_exp_f32_e32 v65, v65
	v_exp_f32_e32 v66, v66
	v_exp_f32_e32 v67, v67
	v_exp_f32_e32 v84, v84
	v_exp_f32_e32 v85, v85
	v_exp_f32_e32 v86, v86
	v_exp_f32_e32 v87, v87
	s_nop 0
	v_pk_add_f32 v[72:73], v[54:55], v[56:57]
	v_pk_add_f32 v[74:75], v[58:59], v[60:61]
	v_pk_add_f32 v[76:77], v[64:65], v[66:67]
	v_pk_add_f32 v[78:79], v[84:85], v[86:87]
	v_pk_add_f32 v[72:73], v[72:73], v[74:75]
	v_pk_add_f32 v[76:77], v[76:77], v[78:79]
	s_nop 0
	v_pk_add_f32 v[72:73], v[72:73], v[76:77]
	s_nop 0
	v_add_f32_e32 v72, v72, v73
	v_fma_f32 v144, v144, v70, v72
	v_cvt_pk_bf16_f32 v61, v60, v61
	v_cvt_pk_bf16_f32 v60, v58, v59
	v_cvt_pk_bf16_f32 v59, v56, v57
	v_cvt_pk_bf16_f32 v58, v54, v55
	v_cvt_pk_bf16_f32 v54, v64, v65
	v_cvt_pk_bf16_f32 v55, v66, v67
	v_cvt_pk_bf16_f32 v56, v84, v85
	v_cvt_pk_bf16_f32 v57, v86, v87
	v_cndmask_b32_e64 v63, 0, 1, s[42:43]
	v_cmp_ne_u32_e32 vcc, 0, v63
	s_cbranch_vccz .LBB0_445
.Lp0_cb1:
	v_add_u32_e32 v88, 0xfec, v0
	ds_read_b128 v[64:67], v62 offset:16384
	ds_read_b128 v[68:71], v62 offset:18432
	ds_read_b128 v[72:75], v89 offset:16384
	ds_read_b128 v[76:79], v89 offset:18432
	ds_read2_b32 v[90:91], v88 offset1:1
	ds_read2_b32 v[92:93], v88 offset0:2 offset1:3
	ds_read2_b32 v[94:95], v88 offset0:16 offset1:17
	ds_read2_b32 v[96:97], v88 offset0:18 offset1:19
	ds_read2_b32 v[98:99], v88 offset0:32 offset1:33
	ds_read2_b32 v[100:101], v88 offset0:34 offset1:35
	ds_read2_b32 v[154:155], v88 offset0:48 offset1:49
	ds_read2_b32 v[156:157], v88 offset0:50 offset1:51
	s_waitcnt lgkmcnt(8)
	s_setprio 1
	v_mfma_f32_16x16x32_bf16 v[64:67], v[64:67], v[10:13], 0
	v_mfma_f32_16x16x32_bf16 v[68:71], v[68:71], v[10:13], 0
	v_mfma_f32_16x16x32_bf16 v[64:67], v[72:75], v[14:17], v[64:67]
	ds_read_b128 v[72:75], v62 offset:20480
	v_mfma_f32_16x16x32_bf16 v[68:71], v[76:79], v[14:17], v[68:71]
	ds_read_b128 v[76:79], v89 offset:20480
	ds_read_b128 v[80:83], v62 offset:22528
	ds_read_b128 v[84:87], v89 offset:22528
	s_waitcnt lgkmcnt(0)
	v_mfma_f32_16x16x32_bf16 v[72:75], v[72:75], v[10:13], 0
	v_mfma_f32_16x16x32_bf16 v[80:83], v[80:83], v[10:13], 0
	v_mfma_f32_16x16x32_bf16 v[72:75], v[76:79], v[14:17], v[72:75]
	v_mfma_f32_16x16x32_bf16 v[80:83], v[84:87], v[14:17], v[80:83]
	s_setprio 0
	v_pk_fma_f32 v[64:65], v[64:65], s[36:37], v[90:91] op_sel_hi:[1,0,1]
	v_pk_fma_f32 v[66:67], v[66:67], s[36:37], v[92:93] op_sel_hi:[1,0,1]
	v_pk_fma_f32 v[68:69], v[68:69], s[36:37], v[94:95] op_sel_hi:[1,0,1]
	v_pk_fma_f32 v[70:71], v[70:71], s[36:37], v[96:97] op_sel_hi:[1,0,1]
	s_nop 3
	v_pk_fma_f32 v[72:73], v[72:73], s[36:37], v[98:99] op_sel_hi:[1,0,1]
	v_pk_fma_f32 v[74:75], v[74:75], s[36:37], v[100:101] op_sel_hi:[1,0,1]
	v_pk_fma_f32 v[80:81], v[80:81], s[36:37], v[154:155] op_sel_hi:[1,0,1]
	v_pk_fma_f32 v[82:83], v[82:83], s[36:37], v[156:157] op_sel_hi:[1,0,1]
	v_or_b32_e32 v79, s14, v197
	v_sub_u32_e32 v88, v142, v79
	v_cmp_le_i32_e64 s[6:7], 0, v88
	v_cmp_le_i32_e64 s[18:19], 1, v88
	v_cmp_le_i32_e64 s[98:99], 2, v88
	v_cmp_le_i32_e64 s[100:101], 3, v88
	v_cndmask_b32_e64 v64, v148, v64, s[6:7]
	v_cndmask_b32_e64 v65, v148, v65, s[18:19]
	v_cndmask_b32_e64 v66, v148, v66, s[98:99]
	v_cndmask_b32_e64 v67, v148, v67, s[100:101]
	v_cmp_le_i32_e64 s[6:7], 16, v88
	v_cmp_le_i32_e64 s[18:19], 17, v88
	v_cmp_le_i32_e64 s[98:99], 18, v88
	v_cmp_le_i32_e64 s[100:101], 19, v88
	v_cndmask_b32_e64 v68, v148, v68, s[6:7]
	v_cndmask_b32_e64 v69, v148, v69, s[18:19]
	v_cndmask_b32_e64 v70, v148, v70, s[98:99]
	v_cndmask_b32_e64 v71, v148, v71, s[100:101]
	v_cmp_le_i32_e64 s[6:7], 32, v88
	v_cmp_le_i32_e64 s[18:19], 33, v88
	v_cmp_le_i32_e64 s[98:99], 34, v88
	v_cmp_le_i32_e64 s[100:101], 35, v88
	v_cndmask_b32_e64 v72, v148, v72, s[6:7]
	v_cndmask_b32_e64 v73, v148, v73, s[18:19]
	v_cndmask_b32_e64 v74, v148, v74, s[98:99]
	v_cndmask_b32_e64 v75, v148, v75, s[100:101]
	v_cmp_le_i32_e64 s[6:7], 48, v88
	v_cmp_le_i32_e64 s[18:19], 49, v88
	v_cmp_le_i32_e64 s[98:99], 50, v88
	v_cmp_le_i32_e64 s[100:101], 51, v88
	v_cndmask_b32_e64 v80, v148, v80, s[6:7]
	v_cndmask_b32_e64 v81, v148, v81, s[18:19]
	v_cndmask_b32_e64 v82, v148, v82, s[98:99]
	v_cndmask_b32_e64 v83, v148, v83, s[100:101]
	v_max3_f32 v76, v64, v65, v66
	v_max3_f32 v76, v76, v67, v68
	v_max3_f32 v76, v76, v69, v70
	v_max3_f32 v76, v76, v71, v72
	v_max3_f32 v76, v76, v73, v74
	v_max3_f32 v76, v76, v75, v80
	v_max3_f32 v76, v76, v81, v82
	v_max3_f32 v76, v76, v83, s29
	v_mov_b32_e32 v77, v76
	s_nop 1
	v_permlane16_swap_b32_e32 v76, v77
	v_max_f32_e32 v76, v76, v77
	v_mov_b32_e32 v77, v76
	s_nop 1
	v_permlane32_swap_b32_e32 v76, v77
	v_max_f32_e32 v76, v76, v77
	v_cndmask_b32_e64 v76, v148, v76, s[42:43]
	v_max_f32_e32 v77, v161, v76
	v_sub_f32_e32 v0, v161, v77
	v_exp_f32_e32 v0, v0
	v_cndmask_b32_e64 v78, v209, v77, s[42:43]
	v_mov_b32_e32 v161, v77
	v_pk_mul_f32 v[32:33], v[32:33], v[0:1] op_sel_hi:[1,0]
	v_pk_mul_f32 v[30:31], v[30:31], v[0:1] op_sel_hi:[1,0]
	v_pk_mul_f32 v[28:29], v[28:29], v[0:1] op_sel_hi:[1,0]
	v_pk_mul_f32 v[26:27], v[26:27], v[0:1] op_sel_hi:[1,0]
	v_pk_mul_f32 v[24:25], v[24:25], v[0:1] op_sel_hi:[1,0]
	v_pk_mul_f32 v[22:23], v[22:23], v[0:1] op_sel_hi:[1,0]
	v_pk_mul_f32 v[20:21], v[20:21], v[0:1] op_sel_hi:[1,0]
	v_pk_mul_f32 v[18:19], v[18:19], v[0:1] op_sel_hi:[1,0]
	v_pk_add_f32 v[64:65], v[64:65], v[78:79] op_sel_hi:[1,0] neg_lo:[0,1] neg_hi:[0,1]
	v_pk_add_f32 v[66:67], v[66:67], v[78:79] op_sel_hi:[1,0] neg_lo:[0,1] neg_hi:[0,1]
	v_pk_add_f32 v[68:69], v[68:69], v[78:79] op_sel_hi:[1,0] neg_lo:[0,1] neg_hi:[0,1]
	v_pk_add_f32 v[70:71], v[70:71], v[78:79] op_sel_hi:[1,0] neg_lo:[0,1] neg_hi:[0,1]
	v_pk_add_f32 v[72:73], v[72:73], v[78:79] op_sel_hi:[1,0] neg_lo:[0,1] neg_hi:[0,1]
	v_pk_add_f32 v[74:75], v[74:75], v[78:79] op_sel_hi:[1,0] neg_lo:[0,1] neg_hi:[0,1]
	v_pk_add_f32 v[80:81], v[80:81], v[78:79] op_sel_hi:[1,0] neg_lo:[0,1] neg_hi:[0,1]
	v_pk_add_f32 v[82:83], v[82:83], v[78:79] op_sel_hi:[1,0] neg_lo:[0,1] neg_hi:[0,1]
	v_exp_f32_e32 v64, v64
	v_exp_f32_e32 v65, v65
	v_exp_f32_e32 v66, v66
	v_exp_f32_e32 v67, v67
	v_exp_f32_e32 v68, v68
	v_exp_f32_e32 v69, v69
	v_exp_f32_e32 v70, v70
	v_exp_f32_e32 v71, v71
	v_exp_f32_e32 v72, v72
	v_exp_f32_e32 v73, v73
	v_exp_f32_e32 v74, v74
	v_exp_f32_e32 v75, v75
	v_exp_f32_e32 v80, v80
	v_exp_f32_e32 v81, v81
	v_exp_f32_e32 v82, v82
	v_exp_f32_e32 v83, v83
	s_nop 0
	v_pk_add_f32 v[84:85], v[64:65], v[66:67]
	v_pk_add_f32 v[86:87], v[68:69], v[70:71]
	v_pk_add_f32 v[76:77], v[72:73], v[74:75]
	v_pk_add_f32 v[78:79], v[80:81], v[82:83]
	v_pk_add_f32 v[84:85], v[84:85], v[86:87]
	v_pk_add_f32 v[76:77], v[76:77], v[78:79]
	s_nop 0
	v_pk_add_f32 v[84:85], v[84:85], v[76:77]
	s_nop 0
	v_add_f32_e32 v84, v84, v85
	v_fma_f32 v145, v145, v0, v84
	v_cvt_pk_bf16_f32 v67, v66, v67
	v_cvt_pk_bf16_f32 v66, v64, v65
	v_cvt_pk_bf16_f32 v68, v68, v69
	v_cvt_pk_bf16_f32 v69, v70, v71
	v_cvt_pk_bf16_f32 v62, v72, v73
	v_cvt_pk_bf16_f32 v63, v74, v75
	v_cvt_pk_bf16_f32 v64, v80, v81
	v_cvt_pk_bf16_f32 v65, v82, v83
	s_branch .LBB0_446

.LBB0_430:
	s_andn2_b64 vcc, exec, s[6:7]
	s_cbranch_vccnz .LBB0_438
	v_cmp_ne_u32_e32 vcc, 0, v139
	s_cbranch_vccz .Lsel_fast
	v_add_u32_e32 v54, s13, v196
	v_sub_u32_e32 v0, s14, v140
	v_add_u32_e32 v62, v54, v194
	v_add_u32_e32 v89, v54, v195
	v_lshl_add_u32 v0, v0, 2, v216
	s_cmp_lg_u64 s[44:45], 0
	s_movk_i32 s98, 0xfec
	s_cselect_b32 s98, 0xffc, s98
	v_add_u32_e32 v230, s98, v0
	v_add_u32_e32 v231, 0xfec, v0
	ds_read_b128 v[64:67], v62 offset:16384
	ds_read_b128 v[54:57], v89 offset:16384
	ds_read_b128 v[68:71], v62 offset:18432
	ds_read_b128 v[58:61], v89 offset:18432
	ds_read_b128 v[72:75], v62 offset:20480
	ds_read_b128 v[76:79], v89 offset:20480
	ds_read_b128 v[80:83], v62 offset:22528
	ds_read_b128 v[84:87], v89 offset:22528
	ds_read2_b32 v[90:91], v230 offset1:1
	ds_read2_b32 v[92:93], v230 offset0:2 offset1:3
	ds_read2_b32 v[94:95], v230 offset0:16 offset1:17
	ds_read2_b32 v[96:97], v230 offset0:18 offset1:19
	s_waitcnt lgkmcnt(4)
	ds_read2_b32 v[98:99], v230 offset0:32 offset1:33
	ds_read2_b32 v[100:101], v230 offset0:34 offset1:35
	ds_read2_b32 v[154:155], v230 offset0:48 offset1:49
	ds_read2_b32 v[156:157], v230 offset0:50 offset1:51
	s_cbranch_scc0 .Lp1v_m1
	s_setprio 1
	v_mfma_f32_16x16x32_bf16 v[170:173], v[64:67], v[2:5], 0
	v_mfma_f32_16x16x32_bf16 v[174:177], v[68:71], v[2:5], 0
	v_mfma_f32_16x16x32_bf16 v[170:173], v[54:57], v[6:9], v[170:173]
	v_mfma_f32_16x16x32_bf16 v[178:181], v[72:75], v[2:5], 0
	v_mfma_f32_16x16x32_bf16 v[174:177], v[58:61], v[6:9], v[174:177]
	v_mfma_f32_16x16x32_bf16 v[182:185], v[80:83], v[2:5], 0
	v_mfma_f32_16x16x32_bf16 v[178:181], v[76:79], v[6:9], v[178:181]
	v_mfma_f32_16x16x32_bf16 v[182:185], v[84:87], v[6:9], v[182:185]
	s_setprio 0
.Lp1v_m1:
	s_cmp_lg_u64 s[42:43], 0
	s_cbranch_scc0 .Lp1v_nom1
	s_setprio 1
	v_mfma_f32_16x16x32_bf16 v[64:67], v[64:67], v[10:13], 0
	v_mfma_f32_16x16x32_bf16 v[68:71], v[68:71], v[10:13], 0
	v_mfma_f32_16x16x32_bf16 v[64:67], v[54:57], v[14:17], v[64:67]
	v_mfma_f32_16x16x32_bf16 v[72:75], v[72:75], v[10:13], 0
	v_mfma_f32_16x16x32_bf16 v[68:71], v[58:61], v[14:17], v[68:71]
	v_mfma_f32_16x16x32_bf16 v[80:83], v[80:83], v[10:13], 0
	v_mfma_f32_16x16x32_bf16 v[72:75], v[76:79], v[14:17], v[72:75]
	v_mfma_f32_16x16x32_bf16 v[80:83], v[84:87], v[14:17], v[80:83]
	s_setprio 0
	s_branch .Lp1v_s0

.LBB0_439:
	s_andn2_b64 vcc, exec, s[6:7]
	s_cbranch_vccnz .LBB0_448
	v_and_b32_e32 v0, 1, v164
	v_cmp_eq_u32_e64 s[42:43], 1, v0
	v_and_b32_e32 v0, 1, v162
	v_cmp_eq_u32_e64 s[44:45], 1, v0
	s_or_b64 s[6:7], s[44:45], s[42:43]
	v_cndmask_b32_e64 v54, 0, 1, s[6:7]
	v_cmp_ne_u32_e32 vcc, 0, v54
	s_cbranch_vccz .Lsel_fast
	v_add_u32_e32 v54, s13, v196
	v_add_u32_e32 v62, v54, v194
	v_add_u32_e32 v0, v54, v195
	s_cmp_lg_u64 s[44:45], 0
	ds_read_b128 v[64:67], v62 offset:16384
	ds_read_b128 v[54:57], v0 offset:16384
	ds_read_b128 v[68:71], v62 offset:18432
	ds_read_b128 v[58:61], v0 offset:18432
	ds_read_b128 v[72:75], v62 offset:20480
	ds_read_b128 v[76:79], v0 offset:20480
	ds_read_b128 v[80:83], v62 offset:22528
	ds_read_b128 v[84:87], v0 offset:22528
	ds_read_b32 v188, v193
	s_waitcnt lgkmcnt(0)
	s_cbranch_scc0 .Lp2v_m1
	s_setprio 1
	v_mfma_f32_16x16x32_bf16 v[170:173], v[64:67], v[2:5], 0
	v_mfma_f32_16x16x32_bf16 v[174:177], v[68:71], v[2:5], 0
	v_mfma_f32_16x16x32_bf16 v[170:173], v[54:57], v[6:9], v[170:173]
	v_mfma_f32_16x16x32_bf16 v[178:181], v[72:75], v[2:5], 0
	v_mfma_f32_16x16x32_bf16 v[174:177], v[58:61], v[6:9], v[174:177]
	v_mfma_f32_16x16x32_bf16 v[182:185], v[80:83], v[2:5], 0
	v_mfma_f32_16x16x32_bf16 v[178:181], v[76:79], v[6:9], v[178:181]
	v_mfma_f32_16x16x32_bf16 v[182:185], v[84:87], v[6:9], v[182:185]
	s_setprio 0

.LBB0_446:
	v_add3_u32 v0, s13, v198, v199
	v_add_u32_e32 v78, v0, v200
	v_add_u32_e32 v79, v0, v201
	s_waitcnt vmcnt(0)
	ds_read_b64_tr_b16 v[70:71], v78 offset:24576
	ds_read_b64_tr_b16 v[72:73], v78 offset:26624
	ds_read_b64_tr_b16 v[74:75], v79 offset:24576
	ds_read_b64_tr_b16 v[76:77], v79 offset:26624
	v_add_u32_e32 v80, v0, v202
	v_add_u32_e32 v0, v0, v203
	s_waitcnt lgkmcnt(0)
	s_setprio 1
	v_mfma_f32_16x16x32_bf16 v[34:37], v[70:73], v[58:61], v[34:37]
	v_mfma_f32_16x16x32_bf16 v[30:33], v[70:73], v[66:69], v[30:33]
	ds_read_b64_tr_b16 v[70:71], v80 offset:24576
	ds_read_b64_tr_b16 v[72:73], v80 offset:26624
	v_mfma_f32_16x16x32_bf16 v[46:49], v[74:77], v[58:61], v[46:49]
	v_mfma_f32_16x16x32_bf16 v[26:29], v[74:77], v[66:69], v[26:29]
	ds_read_b64_tr_b16 v[74:75], v0 offset:24576
	ds_read_b64_tr_b16 v[76:77], v0 offset:26624
	s_waitcnt lgkmcnt(2)
	v_mfma_f32_16x16x32_bf16 v[42:45], v[70:73], v[58:61], v[42:45]
	v_mfma_f32_16x16x32_bf16 v[22:25], v[70:73], v[66:69], v[22:25]
	s_waitcnt lgkmcnt(0)
	v_mfma_f32_16x16x32_bf16 v[50:53], v[74:77], v[58:61], v[50:53]
	ds_read_b64_tr_b16 v[58:59], v78 offset:28672
	ds_read_b64_tr_b16 v[60:61], v78 offset:30720
	v_mfma_f32_16x16x32_bf16 v[18:21], v[74:77], v[66:69], v[18:21]
	ds_read_b64_tr_b16 v[66:67], v79 offset:28672
	ds_read_b64_tr_b16 v[68:69], v79 offset:30720
	s_waitcnt lgkmcnt(2)
	v_mfma_f32_16x16x32_bf16 v[34:37], v[58:61], v[54:57], v[34:37]
	v_mfma_f32_16x16x32_bf16 v[30:33], v[58:61], v[62:65], v[30:33]
	ds_read_b64_tr_b16 v[58:59], v80 offset:28672
	ds_read_b64_tr_b16 v[60:61], v80 offset:30720
	s_waitcnt lgkmcnt(2)
	v_mfma_f32_16x16x32_bf16 v[46:49], v[66:69], v[54:57], v[46:49]
	v_mfma_f32_16x16x32_bf16 v[26:29], v[66:69], v[62:65], v[26:29]
	ds_read_b64_tr_b16 v[66:67], v0 offset:28672
	ds_read_b64_tr_b16 v[68:69], v0 offset:30720
	s_waitcnt lgkmcnt(2)
	v_mfma_f32_16x16x32_bf16 v[42:45], v[58:61], v[54:57], v[42:45]
	v_mfma_f32_16x16x32_bf16 v[22:25], v[58:61], v[62:65], v[22:25]
	s_waitcnt lgkmcnt(0)
	v_mfma_f32_16x16x32_bf16 v[50:53], v[66:69], v[54:57], v[50:53]
	v_mfma_f32_16x16x32_bf16 v[18:21], v[66:69], v[62:65], v[18:21]
	s_setprio 0
	s_branch .Lsel_fast
